# MLA loop: softmax finalisation (permlane max, rescale compare) moved inside MFMA slots 18-19, LDS stores/loads of the staging set at slots 14-16, rescale compare issued before the barrier
# speedup vs baseline: 1.0197x; 1.0084x over previous
; template <int VAR>
; __device__ __forceinline__ void attn_phase(LAS unsigned char* lds, const AttnP P, int vcu, int G, int wave_s) {
;     ...
;                 if (ND0 == 6) {
;                     KR1(0); KR1(1); KR1(2); KR1(3); SB();
;                     QK1(0, negm); EX2(pc0, 0, w0.x); KR1(4); SB();
;                     QK1(1, negm); EX2(pc0, 2, w0.y); KR1(5); SB();
;                     QK1(2, pn0); EX2(pc0, 4, w0.z); KR1(6); SB();
;                     QK1(3, pn1); EX2(pc0, 6, w0.w); KR1(7); SB();
;                     QK1(4, pn0); EX2(pc0, 8, w1.x); KR1(8); SB();
;                     QK1(5, pn1); EX2(pc0, 10, w1.y); KR1(9); SB();
;                     QK1(6, pn0); EX2(pc0, 12, w1.z); KR1(10); SB();
;                     QK1(7, pn1); EX2(pc0, 14, w1.w); KR1(11); SB();
;                     QK1(8, pn0); EX2(pc1, 0, w2.x); VR1(0); SB();
;                     QK1(9, pn1); EX2(pc1, 2, w2.y); VR1(1); SB();
;                     QK1(10, pn0); EX2(pc1, 4, w2.z); VR1(2); SB();
;                     QK1(11, pn1); EX2(pc1, 6, w2.w); VR1(3); SB();
;                 } else {
;                     KR1(0); KR1(1); KR1(2); KR1(3); SB();
;                     QK1(0, negm); EX2(pc0, 0, w0.x); EX2(pc0, 2, w0.y); KR1(4); SB();
;                     QK1(1, negm); EX2(pc0, 4, w0.z); EX2(pc0, 6, w0.w); KR1(5); SB();
;                     QK1(2, pn0); EX2(pc0, 8, w1.x); EX2(pc0, 10, w1.y); KR1(6); SB();
;                     QK1(3, pn1); EX2(pc0, 12, w1.z); EX2(pc0, 14, w1.w); KR1(7); SB();
;                     QK1(4, pn0); EX2(pc1, 0, w2.x); VR1(0); SB();
;                     QK1(5, pn1); EX2(pc1, 2, w2.y); VR1(1); SB();
;                     QK1(6, pn0); EX2(pc1, 4, w2.z); VR1(2); SB();
;                     QK1(7, pn1); EX2(pc1, 6, w2.w); VR1(3); SB();
;                 }
;                 PV1(0, w0); EX2(pc1, 8, w3.x); VR1(4); SB();
;                 PV1(1, w0); EX2(pc1, 10, w3.y); VR1(5); SB();
;                 PV1(2, w1); EX2(pc1, 12, w3.z); VR1(6); SB();
;                 PV1(3, w1); EX2(pc1, 14, w3.w); VR1(7); SB();
;                 lrun += sacc;
;                 PV1(4, w2); MASK_TILE(pn0, pn1, t + 1); SB();
;                 PV1(5, w2); SB();
;                 PV1(6, w3); SB();
;                 PV1(7, w3); rmn = rowmax32(pn0, pn1); if (!USE_NEGM) rmn -= mref; SB();
;     ...
;             if (hn) { STOREK(t & 1); STOREV((t + 1) & 1); }
;             __syncthreads();
.Lmla_noprio:
	s_waitcnt lgkmcnt(0)
	s_barrier
	ds_read_b128 v[182:185], v174 offset:22528
	ds_read_b128 v[186:189], v174 offset:29184
	ds_read_b128 v[190:193], v174 offset:22560
	ds_read_b128 v[194:197], v174 offset:29216
	v_cmp_lt_f32_e32 vcc, s66, v167
.Lmla_p0:
	s_cbranch_vccnz .Lmla_p0_resc
.Lmla_p0_go:
	v_exp_f32_e32 v222, v34
	v_exp_f32_e32 v223, v35
	v_add_f32_e32 v164, 0, v222
	v_cvt_pk_bf16_f32 v206, v222, v223
	v_add_f32_e32 v164, v223, v164
	v_exp_f32_e32 v224, v36
	v_exp_f32_e32 v225, v37
	v_add_f32_e32 v164, v224, v164
	v_cvt_pk_bf16_f32 v207, v224, v225
	v_add_f32_e32 v164, v225, v164
	s_waitcnt lgkmcnt(3)
	v_mfma_f32_32x32x16_bf16 v[82:97], v[182:185], v[114:117], v[66:81]
	ds_read_b128 v[198:201], v174 offset:22592
	v_exp_f32_e32 v222, v38
	v_exp_f32_e32 v223, v39
	v_add_f32_e32 v164, v222, v164
	v_cvt_pk_bf16_f32 v208, v222, v223
	v_add_f32_e32 v164, v223, v164
	s_waitcnt lgkmcnt(3)
	v_mfma_f32_32x32x16_bf16 v[98:113], v[186:189], v[114:117], v[66:81]
	ds_read_b128 v[182:185], v174 offset:29248
	v_exp_f32_e32 v224, v40
	v_exp_f32_e32 v225, v41
	v_add_f32_e32 v164, v224, v164
	v_cvt_pk_bf16_f32 v209, v224, v225
	v_add_f32_e32 v164, v225, v164
	s_waitcnt lgkmcnt(3)
	v_mfma_f32_32x32x16_bf16 v[82:97], v[190:193], v[118:121], v[82:97]
	ds_read_b128 v[186:189], v174 offset:22624
	v_exp_f32_e32 v222, v42
	v_exp_f32_e32 v223, v43
	v_add_f32_e32 v164, v222, v164
	v_cvt_pk_bf16_f32 v210, v222, v223
	v_add_f32_e32 v164, v223, v164
	s_waitcnt lgkmcnt(3)
	v_mfma_f32_32x32x16_bf16 v[98:113], v[194:197], v[118:121], v[98:113]
	ds_read_b128 v[190:193], v174 offset:29280
	v_exp_f32_e32 v224, v44
	v_exp_f32_e32 v225, v45
	v_add_f32_e32 v164, v224, v164
	v_cvt_pk_bf16_f32 v211, v224, v225
	v_add_f32_e32 v164, v225, v164
	s_waitcnt lgkmcnt(3)
	v_mfma_f32_32x32x16_bf16 v[82:97], v[198:201], v[122:125], v[82:97]
	ds_read_b128 v[194:197], v174 offset:22656
	v_exp_f32_e32 v222, v46
	v_exp_f32_e32 v223, v47
	v_add_f32_e32 v164, v222, v164
	v_cvt_pk_bf16_f32 v212, v222, v223
	v_add_f32_e32 v164, v223, v164
	s_waitcnt lgkmcnt(3)
	v_mfma_f32_32x32x16_bf16 v[98:113], v[182:185], v[122:125], v[98:113]
	ds_read_b128 v[198:201], v174 offset:29312
	v_exp_f32_e32 v224, v48
	v_exp_f32_e32 v225, v49
	v_add_f32_e32 v164, v224, v164
	v_cvt_pk_bf16_f32 v213, v224, v225
	v_add_f32_e32 v164, v225, v164
	s_waitcnt lgkmcnt(3)
	v_mfma_f32_32x32x16_bf16 v[82:97], v[186:189], v[126:129], v[82:97]
	ds_read_b128 v[182:185], v174 offset:22688
	v_exp_f32_e32 v222, v50
	v_exp_f32_e32 v223, v51
	v_add_f32_e32 v164, v222, v164
	v_cvt_pk_bf16_f32 v214, v222, v223
	v_add_f32_e32 v164, v223, v164
	s_waitcnt lgkmcnt(3)
	v_mfma_f32_32x32x16_bf16 v[98:113], v[190:193], v[126:129], v[98:113]
	ds_read_b128 v[186:189], v174 offset:29344
	v_exp_f32_e32 v224, v52
	v_exp_f32_e32 v225, v53
	v_add_f32_e32 v164, v224, v164
	v_cvt_pk_bf16_f32 v215, v224, v225
	v_add_f32_e32 v164, v225, v164
	s_waitcnt lgkmcnt(3)
	v_mfma_f32_32x32x16_bf16 v[82:97], v[194:197], v[130:133], v[82:97]
	ds_read_b128 v[190:193], v228 offset:13312
	v_exp_f32_e32 v222, v54
	v_exp_f32_e32 v223, v55
	v_add_f32_e32 v164, v222, v164
	v_cvt_pk_bf16_f32 v216, v222, v223
	v_add_f32_e32 v164, v223, v164
	s_waitcnt lgkmcnt(3)
	v_mfma_f32_32x32x16_bf16 v[98:113], v[198:201], v[130:133], v[98:113]
	ds_read_b128 v[194:197], v228 offset:17920
	v_exp_f32_e32 v224, v56
	v_exp_f32_e32 v225, v57
	v_add_f32_e32 v164, v224, v164
	v_cvt_pk_bf16_f32 v217, v224, v225
	v_add_f32_e32 v164, v225, v164
	s_waitcnt lgkmcnt(3)
	v_mfma_f32_32x32x16_bf16 v[82:97], v[182:185], v[134:137], v[82:97]
	ds_read_b128 v[198:201], v228 offset:13344
	v_exp_f32_e32 v222, v58
	v_exp_f32_e32 v223, v59
	v_add_f32_e32 v164, v222, v164
	v_cvt_pk_bf16_f32 v218, v222, v223
	v_add_f32_e32 v164, v223, v164
	s_waitcnt lgkmcnt(3)
	v_mfma_f32_32x32x16_bf16 v[98:113], v[186:189], v[134:137], v[98:113]
	ds_read_b128 v[182:185], v228 offset:17952
	v_exp_f32_e32 v224, v60
	v_exp_f32_e32 v225, v61
	v_add_f32_e32 v164, v224, v164
	v_cvt_pk_bf16_f32 v219, v224, v225
	v_add_f32_e32 v164, v225, v164
	s_waitcnt lgkmcnt(3)
	v_mfma_f32_32x32x16_bf16 v[2:17], v[190:193], v[206:209], v[2:17]
	ds_read_b128 v[186:189], v228 offset:13376
	v_exp_f32_e32 v222, v62
	v_exp_f32_e32 v223, v63
	v_add_f32_e32 v164, v222, v164
	v_cvt_pk_bf16_f32 v220, v222, v223
	v_add_f32_e32 v164, v223, v164
	s_waitcnt lgkmcnt(3)
	v_mfma_f32_32x32x16_bf16 v[18:33], v[194:197], v[206:209], v[18:33]
	ds_read_b128 v[190:193], v228 offset:17984
	v_exp_f32_e32 v224, v64
	v_exp_f32_e32 v225, v65
	v_add_f32_e32 v164, v224, v164
	v_cvt_pk_bf16_f32 v221, v224, v225
	v_add_f32_e32 v164, v225, v164
	s_mov_b32 s13, s19
	s_add_i32 s19, s19, 1
	s_cmp_eq_u32 s19, s9
	s_cselect_b32 s19, 0, s19
	s_waitcnt lgkmcnt(3)
	v_mfma_f32_32x32x16_bf16 v[2:17], v[198:201], v[210:213], v[2:17]
	ds_read_b128 v[194:197], v228 offset:13408
	v_max3_f32 v224, v82, v83, v84
	v_max3_f32 v225, v98, v99, v100
	v_max3_f32 v224, v224, v85, v86
	v_max3_f32 v225, v225, v101, v102
	s_waitcnt vmcnt(2)
	v_add_u32_e32 v222, 0xb000, v172
	ds_write_b128 v222, v[146:149] offset:22528
	v_lshl_add_u32 v222, s19, 17, v178
	global_load_dwordx4 v[146:149], v222, s[52:53]
	s_waitcnt lgkmcnt(4)
	v_mfma_f32_32x32x16_bf16 v[18:33], v[182:185], v[210:213], v[18:33]
	ds_read_b128 v[198:201], v228 offset:18016
	v_max3_f32 v224, v224, v87, v88
	v_max3_f32 v225, v225, v103, v104
	v_max3_f32 v224, v224, v89, v90
	v_max3_f32 v225, v225, v105, v106
	s_and_b64 vcc, exec, s[2:3]
	s_cbranch_vccz .Lmla_p0_nope
	v_add_u32_e32 v222, 0xb000, v176
	ds_write_b128 v222, v[138:141] offset:22656
	v_lshl_add_u32 v222, s19, 12, v179
	global_load_dwordx4 v[138:141], v222, s[62:63]
.Lmla_p0_nope:
	s_waitcnt lgkmcnt(4)
	v_mfma_f32_32x32x16_bf16 v[2:17], v[186:189], v[214:217], v[2:17]
	ds_read_b128 v[182:185], v229
	v_max3_f32 v224, v224, v91, v92
	v_max3_f32 v225, v225, v107, v108
	v_max3_f32 v224, v224, v93, v94
	v_max3_f32 v225, v225, v109, v110
	ds_write_b128 v173, v[142:145] offset:58368
	v_lshl_add_u32 v222, s13, 7, v168
	global_load_dwordx4 v[142:145], v222, s[56:57]
	s_waitcnt lgkmcnt(5)
	v_mfma_f32_32x32x16_bf16 v[18:33], v[190:193], v[214:217], v[18:33]
	ds_read_b128 v[186:189], v229 offset:6656
	v_max3_f32 v224, v224, v95, v96
	v_max3_f32 v225, v225, v111, v112
	v_max3_f32 v224, v224, v97, v113
	v_max_f32_e32 v224, v224, v225
	s_waitcnt lgkmcnt(5)
	v_mfma_f32_32x32x16_bf16 v[2:17], v[194:197], v[218:221], v[2:17]
	ds_read_b128 v[190:193], v229 offset:32
	v_mov_b32_e32 v225, v224
	v_add_f32_e32 v1, v1, v164
	s_add_i32 s11, s11, 1
	v_permlane32_swap_b32_e32 v224, v225
	s_cmp_eq_u32 s9, s11
	v_max_f32_e32 v167, v224, v225
	s_waitcnt lgkmcnt(4)
	v_mfma_f32_32x32x16_bf16 v[18:33], v[198:201], v[218:221], v[18:33]
	ds_read_b128 v[194:197], v229 offset:6688
	v_cmp_lt_f32_e32 vcc, s66, v167
	s_waitcnt lgkmcnt(3)
	s_barrier
	s_cbranch_scc1 .Lmla_exit_p0

; template <int VAR>
; __device__ __forceinline__ void attn_phase(LAS unsigned char* lds, const AttnP P, int vcu, int G, int wave_s) {
;     ...
;                 if (ND0 == 6) {
;                     KR1(0); KR1(1); KR1(2); KR1(3); SB();
;                     QK1(0, negm); EX2(pc0, 0, w0.x); KR1(4); SB();
;                     QK1(1, negm); EX2(pc0, 2, w0.y); KR1(5); SB();
;                     QK1(2, pn0); EX2(pc0, 4, w0.z); KR1(6); SB();
;                     QK1(3, pn1); EX2(pc0, 6, w0.w); KR1(7); SB();
;                     QK1(4, pn0); EX2(pc0, 8, w1.x); KR1(8); SB();
;                     QK1(5, pn1); EX2(pc0, 10, w1.y); KR1(9); SB();
;                     QK1(6, pn0); EX2(pc0, 12, w1.z); KR1(10); SB();
;                     QK1(7, pn1); EX2(pc0, 14, w1.w); KR1(11); SB();
;                     QK1(8, pn0); EX2(pc1, 0, w2.x); VR1(0); SB();
;                     QK1(9, pn1); EX2(pc1, 2, w2.y); VR1(1); SB();
;                     QK1(10, pn0); EX2(pc1, 4, w2.z); VR1(2); SB();
;                     QK1(11, pn1); EX2(pc1, 6, w2.w); VR1(3); SB();
;                 } else {
;                     KR1(0); KR1(1); KR1(2); KR1(3); SB();
;                     QK1(0, negm); EX2(pc0, 0, w0.x); EX2(pc0, 2, w0.y); KR1(4); SB();
;                     QK1(1, negm); EX2(pc0, 4, w0.z); EX2(pc0, 6, w0.w); KR1(5); SB();
;                     QK1(2, pn0); EX2(pc0, 8, w1.x); EX2(pc0, 10, w1.y); KR1(6); SB();
;                     QK1(3, pn1); EX2(pc0, 12, w1.z); EX2(pc0, 14, w1.w); KR1(7); SB();
;                     QK1(4, pn0); EX2(pc1, 0, w2.x); VR1(0); SB();
;                     QK1(5, pn1); EX2(pc1, 2, w2.y); VR1(1); SB();
;                     QK1(6, pn0); EX2(pc1, 4, w2.z); VR1(2); SB();
;                     QK1(7, pn1); EX2(pc1, 6, w2.w); VR1(3); SB();
;                 }
;                 PV1(0, w0); EX2(pc1, 8, w3.x); VR1(4); SB();
;                 PV1(1, w0); EX2(pc1, 10, w3.y); VR1(5); SB();
;                 PV1(2, w1); EX2(pc1, 12, w3.z); VR1(6); SB();
;                 PV1(3, w1); EX2(pc1, 14, w3.w); VR1(7); SB();
;                 lrun += sacc;
;                 PV1(4, w2); MASK_TILE(pn0, pn1, t + 1); SB();
;                 PV1(5, w2); SB();
;                 PV1(6, w3); SB();
;                 PV1(7, w3); rmn = rowmax32(pn0, pn1); if (!USE_NEGM) rmn -= mref; SB();
;     ...
;             if (hn) { STOREK(t & 1); STOREV((t + 1) & 1); }
;             __syncthreads();
.Lmla_p1_go:
	v_exp_f32_e32 v222, v82
	v_exp_f32_e32 v223, v83
	v_add_f32_e32 v164, 0, v222
	v_cvt_pk_bf16_f32 v206, v222, v223
	v_add_f32_e32 v164, v223, v164
	v_exp_f32_e32 v224, v84
	v_exp_f32_e32 v225, v85
	v_add_f32_e32 v164, v224, v164
	v_cvt_pk_bf16_f32 v207, v224, v225
	v_add_f32_e32 v164, v225, v164
	s_waitcnt lgkmcnt(3)
	v_mfma_f32_32x32x16_bf16 v[34:49], v[182:185], v[114:117], v[66:81]
	ds_read_b128 v[198:201], v229 offset:64
	v_exp_f32_e32 v222, v86
	v_exp_f32_e32 v223, v87
	v_add_f32_e32 v164, v222, v164
	v_cvt_pk_bf16_f32 v208, v222, v223
	v_add_f32_e32 v164, v223, v164
	s_waitcnt lgkmcnt(3)
	v_mfma_f32_32x32x16_bf16 v[50:65], v[186:189], v[114:117], v[66:81]
	ds_read_b128 v[182:185], v229 offset:6720
	v_exp_f32_e32 v224, v88
	v_exp_f32_e32 v225, v89
	v_add_f32_e32 v164, v224, v164
	v_cvt_pk_bf16_f32 v209, v224, v225
	v_add_f32_e32 v164, v225, v164
	s_waitcnt lgkmcnt(3)
	v_mfma_f32_32x32x16_bf16 v[34:49], v[190:193], v[118:121], v[34:49]
	ds_read_b128 v[186:189], v229 offset:96
	v_exp_f32_e32 v222, v90
	v_exp_f32_e32 v223, v91
	v_add_f32_e32 v164, v222, v164
	v_cvt_pk_bf16_f32 v210, v222, v223
	v_add_f32_e32 v164, v223, v164
	s_waitcnt lgkmcnt(3)
	v_mfma_f32_32x32x16_bf16 v[50:65], v[194:197], v[118:121], v[50:65]
	ds_read_b128 v[190:193], v229 offset:6752
	v_exp_f32_e32 v224, v92
	v_exp_f32_e32 v225, v93
	v_add_f32_e32 v164, v224, v164
	v_cvt_pk_bf16_f32 v211, v224, v225
	v_add_f32_e32 v164, v225, v164
	s_waitcnt lgkmcnt(3)
	v_mfma_f32_32x32x16_bf16 v[34:49], v[198:201], v[122:125], v[34:49]
	ds_read_b128 v[194:197], v229 offset:128
	v_exp_f32_e32 v222, v94
	v_exp_f32_e32 v223, v95
	v_add_f32_e32 v164, v222, v164
	v_cvt_pk_bf16_f32 v212, v222, v223
	v_add_f32_e32 v164, v223, v164
	s_waitcnt lgkmcnt(3)
	v_mfma_f32_32x32x16_bf16 v[50:65], v[182:185], v[122:125], v[50:65]
	ds_read_b128 v[198:201], v229 offset:6784
	v_exp_f32_e32 v224, v96
	v_exp_f32_e32 v225, v97
	v_add_f32_e32 v164, v224, v164
	v_cvt_pk_bf16_f32 v213, v224, v225
	v_add_f32_e32 v164, v225, v164
	s_waitcnt lgkmcnt(3)
	v_mfma_f32_32x32x16_bf16 v[34:49], v[186:189], v[126:129], v[34:49]
	ds_read_b128 v[182:185], v229 offset:160
	v_exp_f32_e32 v222, v98
	v_exp_f32_e32 v223, v99
	v_add_f32_e32 v164, v222, v164
	v_cvt_pk_bf16_f32 v214, v222, v223
	v_add_f32_e32 v164, v223, v164
	s_waitcnt lgkmcnt(3)
	v_mfma_f32_32x32x16_bf16 v[50:65], v[190:193], v[126:129], v[50:65]
	ds_read_b128 v[186:189], v229 offset:6816
	v_exp_f32_e32 v224, v100
	v_exp_f32_e32 v225, v101
	v_add_f32_e32 v164, v224, v164
	v_cvt_pk_bf16_f32 v215, v224, v225
	v_add_f32_e32 v164, v225, v164
	s_waitcnt lgkmcnt(3)
	v_mfma_f32_32x32x16_bf16 v[34:49], v[194:197], v[130:133], v[34:49]
	ds_read_b128 v[190:193], v228 offset:35840
	v_exp_f32_e32 v222, v102
	v_exp_f32_e32 v223, v103
	v_add_f32_e32 v164, v222, v164
	v_cvt_pk_bf16_f32 v216, v222, v223
	v_add_f32_e32 v164, v223, v164
	s_waitcnt lgkmcnt(3)
	v_mfma_f32_32x32x16_bf16 v[50:65], v[198:201], v[130:133], v[50:65]
	ds_read_b128 v[194:197], v228 offset:40448
	v_exp_f32_e32 v224, v104
	v_exp_f32_e32 v225, v105
	v_add_f32_e32 v164, v224, v164
	v_cvt_pk_bf16_f32 v217, v224, v225
	v_add_f32_e32 v164, v225, v164
	s_waitcnt lgkmcnt(3)
	v_mfma_f32_32x32x16_bf16 v[34:49], v[182:185], v[134:137], v[34:49]
	ds_read_b128 v[198:201], v228 offset:35872
	v_exp_f32_e32 v222, v106
	v_exp_f32_e32 v223, v107
	v_add_f32_e32 v164, v222, v164
	v_cvt_pk_bf16_f32 v218, v222, v223
	v_add_f32_e32 v164, v223, v164
	s_waitcnt lgkmcnt(3)
	v_mfma_f32_32x32x16_bf16 v[50:65], v[186:189], v[134:137], v[50:65]
	ds_read_b128 v[182:185], v228 offset:40480
	v_exp_f32_e32 v224, v108
	v_exp_f32_e32 v225, v109
	v_add_f32_e32 v164, v224, v164
	v_cvt_pk_bf16_f32 v219, v224, v225
	v_add_f32_e32 v164, v225, v164
	s_waitcnt lgkmcnt(3)
	v_mfma_f32_32x32x16_bf16 v[2:17], v[190:193], v[206:209], v[2:17]
	ds_read_b128 v[186:189], v228 offset:35904
	v_exp_f32_e32 v222, v110
	v_exp_f32_e32 v223, v111
	v_add_f32_e32 v164, v222, v164
	v_cvt_pk_bf16_f32 v220, v222, v223
	v_add_f32_e32 v164, v223, v164
	s_waitcnt lgkmcnt(3)
	v_mfma_f32_32x32x16_bf16 v[18:33], v[194:197], v[206:209], v[18:33]
	ds_read_b128 v[190:193], v228 offset:40512
	v_exp_f32_e32 v224, v112
	v_exp_f32_e32 v225, v113
	v_add_f32_e32 v164, v224, v164
	v_cvt_pk_bf16_f32 v221, v224, v225
	v_add_f32_e32 v164, v225, v164
	s_mov_b32 s13, s19
	s_add_i32 s19, s19, 1
	s_cmp_eq_u32 s19, s9
	s_cselect_b32 s19, 0, s19
	s_waitcnt lgkmcnt(3)
	v_mfma_f32_32x32x16_bf16 v[2:17], v[198:201], v[210:213], v[2:17]
	ds_read_b128 v[194:197], v228 offset:35936
	v_max3_f32 v224, v34, v35, v36
	v_max3_f32 v225, v50, v51, v52
	v_max3_f32 v224, v224, v37, v38
	v_max3_f32 v225, v225, v53, v54
	s_waitcnt vmcnt(2)
	ds_write_b128 v172, v[150:153]
	v_lshl_add_u32 v222, s19, 17, v178
	global_load_dwordx4 v[150:153], v222, s[52:53]
	s_waitcnt lgkmcnt(4)
	v_mfma_f32_32x32x16_bf16 v[18:33], v[182:185], v[210:213], v[18:33]
	ds_read_b128 v[198:201], v228 offset:40544
	v_max3_f32 v224, v224, v39, v40
	v_max3_f32 v225, v225, v55, v56
	v_max3_f32 v224, v224, v41, v42
	v_max3_f32 v225, v225, v57, v58
	s_and_b64 vcc, exec, s[2:3]
	s_cbranch_vccz .Lmla_p1_nope
	ds_write_b128 v176, v[160:163] offset:128
	v_lshl_add_u32 v222, s19, 12, v179
	global_load_dwordx4 v[160:163], v222, s[62:63]
.Lmla_p1_nope:
	s_waitcnt lgkmcnt(4)
	v_mfma_f32_32x32x16_bf16 v[2:17], v[186:189], v[214:217], v[2:17]
	ds_read_b128 v[182:185], v229 offset:22528
	v_max3_f32 v224, v224, v43, v44
	v_max3_f32 v225, v225, v59, v60
	v_max3_f32 v224, v224, v45, v46
	v_max3_f32 v225, v225, v61, v62
	v_add_u32_e32 v222, 0xb000, v173
	ds_write_b128 v222, v[202:205] offset:35840
	v_lshl_add_u32 v222, s13, 7, v168
	global_load_dwordx4 v[202:205], v222, s[56:57]
	s_waitcnt lgkmcnt(5)
	v_mfma_f32_32x32x16_bf16 v[18:33], v[190:193], v[214:217], v[18:33]
	ds_read_b128 v[186:189], v229 offset:29184
	v_max3_f32 v224, v224, v47, v48
	v_max3_f32 v225, v225, v63, v64
	v_max3_f32 v224, v224, v49, v65
	v_max_f32_e32 v224, v224, v225
	s_waitcnt lgkmcnt(5)
	v_mfma_f32_32x32x16_bf16 v[2:17], v[194:197], v[218:221], v[2:17]
	ds_read_b128 v[190:193], v229 offset:22560
	v_mov_b32_e32 v225, v224
	v_add_f32_e32 v1, v1, v164
	s_add_i32 s11, s11, 1
	v_permlane32_swap_b32_e32 v224, v225
	s_cmp_eq_u32 s9, s11
	v_max_f32_e32 v167, v224, v225
	s_waitcnt lgkmcnt(4)
	v_mfma_f32_32x32x16_bf16 v[18:33], v[198:201], v[218:221], v[18:33]
	ds_read_b128 v[194:197], v229 offset:29216
	v_cmp_lt_f32_e32 vcc, s66, v167
	s_waitcnt lgkmcnt(3)
	s_barrier
	s_cbranch_scc1 .Lmla_exit_p1

; template <int VAR>
; __device__ __forceinline__ void attn_phase(LAS unsigned char* lds, const AttnP P, int vcu, int G, int wave_s) {
;     ...
;                 if (ND0 == 6) {
;                     KR1(0); KR1(1); KR1(2); KR1(3); SB();
;                     QK1(0, negm); EX2(pc0, 0, w0.x); KR1(4); SB();
;                     QK1(1, negm); EX2(pc0, 2, w0.y); KR1(5); SB();
;                     QK1(2, pn0); EX2(pc0, 4, w0.z); KR1(6); SB();
;                     QK1(3, pn1); EX2(pc0, 6, w0.w); KR1(7); SB();
;                     QK1(4, pn0); EX2(pc0, 8, w1.x); KR1(8); SB();
;                     QK1(5, pn1); EX2(pc0, 10, w1.y); KR1(9); SB();
;                     QK1(6, pn0); EX2(pc0, 12, w1.z); KR1(10); SB();
;                     QK1(7, pn1); EX2(pc0, 14, w1.w); KR1(11); SB();
;                     QK1(8, pn0); EX2(pc1, 0, w2.x); VR1(0); SB();
;                     QK1(9, pn1); EX2(pc1, 2, w2.y); VR1(1); SB();
;                     QK1(10, pn0); EX2(pc1, 4, w2.z); VR1(2); SB();
;                     QK1(11, pn1); EX2(pc1, 6, w2.w); VR1(3); SB();
;                 } else {
;                     KR1(0); KR1(1); KR1(2); KR1(3); SB();
;                     QK1(0, negm); EX2(pc0, 0, w0.x); EX2(pc0, 2, w0.y); KR1(4); SB();
;                     QK1(1, negm); EX2(pc0, 4, w0.z); EX2(pc0, 6, w0.w); KR1(5); SB();
;                     QK1(2, pn0); EX2(pc0, 8, w1.x); EX2(pc0, 10, w1.y); KR1(6); SB();
;                     QK1(3, pn1); EX2(pc0, 12, w1.z); EX2(pc0, 14, w1.w); KR1(7); SB();
;                     QK1(4, pn0); EX2(pc1, 0, w2.x); VR1(0); SB();
;                     QK1(5, pn1); EX2(pc1, 2, w2.y); VR1(1); SB();
;                     QK1(6, pn0); EX2(pc1, 4, w2.z); VR1(2); SB();
;                     QK1(7, pn1); EX2(pc1, 6, w2.w); VR1(3); SB();
;                 }
;                 PV1(0, w0); EX2(pc1, 8, w3.x); VR1(4); SB();
;                 PV1(1, w0); EX2(pc1, 10, w3.y); VR1(5); SB();
;                 PV1(2, w1); EX2(pc1, 12, w3.z); VR1(6); SB();
;                 PV1(3, w1); EX2(pc1, 14, w3.w); VR1(7); SB();
;                 lrun += sacc;
;                 PV1(4, w2); MASK_TILE(pn0, pn1, t + 1); SB();
;                 PV1(5, w2); SB();
;                 PV1(6, w3); SB();
;                 PV1(7, w3); rmn = rowmax32(pn0, pn1); if (!USE_NEGM) rmn -= mref; SB();
;     ...
;             if (hn) { STOREK(t & 1); STOREV((t + 1) & 1); }
;             __syncthreads();
.Lmla_p2_go:
	v_exp_f32_e32 v222, v34
	v_exp_f32_e32 v223, v35
	v_add_f32_e32 v164, 0, v222
	v_cvt_pk_bf16_f32 v206, v222, v223
	v_add_f32_e32 v164, v223, v164
	v_exp_f32_e32 v224, v36
	v_exp_f32_e32 v225, v37
	v_add_f32_e32 v164, v224, v164
	v_cvt_pk_bf16_f32 v207, v224, v225
	v_add_f32_e32 v164, v225, v164
	s_waitcnt lgkmcnt(3)
	v_mfma_f32_32x32x16_bf16 v[82:97], v[182:185], v[114:117], v[66:81]
	ds_read_b128 v[198:201], v229 offset:22592
	v_exp_f32_e32 v222, v38
	v_exp_f32_e32 v223, v39
	v_add_f32_e32 v164, v222, v164
	v_cvt_pk_bf16_f32 v208, v222, v223
	v_add_f32_e32 v164, v223, v164
	s_waitcnt lgkmcnt(3)
	v_mfma_f32_32x32x16_bf16 v[98:113], v[186:189], v[114:117], v[66:81]
	ds_read_b128 v[182:185], v229 offset:29248
	v_exp_f32_e32 v224, v40
	v_exp_f32_e32 v225, v41
	v_add_f32_e32 v164, v224, v164
	v_cvt_pk_bf16_f32 v209, v224, v225
	v_add_f32_e32 v164, v225, v164
	s_waitcnt lgkmcnt(3)
	v_mfma_f32_32x32x16_bf16 v[82:97], v[190:193], v[118:121], v[82:97]
	ds_read_b128 v[186:189], v229 offset:22624
	v_exp_f32_e32 v222, v42
	v_exp_f32_e32 v223, v43
	v_add_f32_e32 v164, v222, v164
	v_cvt_pk_bf16_f32 v210, v222, v223
	v_add_f32_e32 v164, v223, v164
	s_waitcnt lgkmcnt(3)
	v_mfma_f32_32x32x16_bf16 v[98:113], v[194:197], v[118:121], v[98:113]
	ds_read_b128 v[190:193], v229 offset:29280
	v_exp_f32_e32 v224, v44
	v_exp_f32_e32 v225, v45
	v_add_f32_e32 v164, v224, v164
	v_cvt_pk_bf16_f32 v211, v224, v225
	v_add_f32_e32 v164, v225, v164
	s_waitcnt lgkmcnt(3)
	v_mfma_f32_32x32x16_bf16 v[82:97], v[198:201], v[122:125], v[82:97]
	ds_read_b128 v[194:197], v229 offset:22656
	v_exp_f32_e32 v222, v46
	v_exp_f32_e32 v223, v47
	v_add_f32_e32 v164, v222, v164
	v_cvt_pk_bf16_f32 v212, v222, v223
	v_add_f32_e32 v164, v223, v164
	s_waitcnt lgkmcnt(3)
	v_mfma_f32_32x32x16_bf16 v[98:113], v[182:185], v[122:125], v[98:113]
	ds_read_b128 v[198:201], v229 offset:29312
	v_exp_f32_e32 v224, v48
	v_exp_f32_e32 v225, v49
	v_add_f32_e32 v164, v224, v164
	v_cvt_pk_bf16_f32 v213, v224, v225
	v_add_f32_e32 v164, v225, v164
	s_waitcnt lgkmcnt(3)
	v_mfma_f32_32x32x16_bf16 v[82:97], v[186:189], v[126:129], v[82:97]
	ds_read_b128 v[182:185], v229 offset:22688
	v_exp_f32_e32 v222, v50
	v_exp_f32_e32 v223, v51
	v_add_f32_e32 v164, v222, v164
	v_cvt_pk_bf16_f32 v214, v222, v223
	v_add_f32_e32 v164, v223, v164
	s_waitcnt lgkmcnt(3)
	v_mfma_f32_32x32x16_bf16 v[98:113], v[190:193], v[126:129], v[98:113]
	ds_read_b128 v[186:189], v229 offset:29344
	v_exp_f32_e32 v224, v52
	v_exp_f32_e32 v225, v53
	v_add_f32_e32 v164, v224, v164
	v_cvt_pk_bf16_f32 v215, v224, v225
	v_add_f32_e32 v164, v225, v164
	s_waitcnt lgkmcnt(3)
	v_mfma_f32_32x32x16_bf16 v[82:97], v[194:197], v[130:133], v[82:97]
	ds_read_b128 v[190:193], v181 offset:13312
	v_exp_f32_e32 v222, v54
	v_exp_f32_e32 v223, v55
	v_add_f32_e32 v164, v222, v164
	v_cvt_pk_bf16_f32 v216, v222, v223
	v_add_f32_e32 v164, v223, v164
	s_waitcnt lgkmcnt(3)
	v_mfma_f32_32x32x16_bf16 v[98:113], v[198:201], v[130:133], v[98:113]
	ds_read_b128 v[194:197], v181 offset:17920
	v_exp_f32_e32 v224, v56
	v_exp_f32_e32 v225, v57
	v_add_f32_e32 v164, v224, v164
	v_cvt_pk_bf16_f32 v217, v224, v225
	v_add_f32_e32 v164, v225, v164
	s_waitcnt lgkmcnt(3)
	v_mfma_f32_32x32x16_bf16 v[82:97], v[182:185], v[134:137], v[82:97]
	ds_read_b128 v[198:201], v181 offset:13344
	v_exp_f32_e32 v222, v58
	v_exp_f32_e32 v223, v59
	v_add_f32_e32 v164, v222, v164
	v_cvt_pk_bf16_f32 v218, v222, v223
	v_add_f32_e32 v164, v223, v164
	s_waitcnt lgkmcnt(3)
	v_mfma_f32_32x32x16_bf16 v[98:113], v[186:189], v[134:137], v[98:113]
	ds_read_b128 v[182:185], v181 offset:17952
	v_exp_f32_e32 v224, v60
	v_exp_f32_e32 v225, v61
	v_add_f32_e32 v164, v224, v164
	v_cvt_pk_bf16_f32 v219, v224, v225
	v_add_f32_e32 v164, v225, v164
	s_waitcnt lgkmcnt(3)
	v_mfma_f32_32x32x16_bf16 v[2:17], v[190:193], v[206:209], v[2:17]
	ds_read_b128 v[186:189], v181 offset:13376
	v_exp_f32_e32 v222, v62
	v_exp_f32_e32 v223, v63
	v_add_f32_e32 v164, v222, v164
	v_cvt_pk_bf16_f32 v220, v222, v223
	v_add_f32_e32 v164, v223, v164
	s_waitcnt lgkmcnt(3)
	v_mfma_f32_32x32x16_bf16 v[18:33], v[194:197], v[206:209], v[18:33]
	ds_read_b128 v[190:193], v181 offset:17984
	v_exp_f32_e32 v224, v64
	v_exp_f32_e32 v225, v65
	v_add_f32_e32 v164, v224, v164
	v_cvt_pk_bf16_f32 v221, v224, v225
	v_add_f32_e32 v164, v225, v164
	s_mov_b32 s13, s19
	s_add_i32 s19, s19, 1
	s_cmp_eq_u32 s19, s9
	s_cselect_b32 s19, 0, s19
	s_waitcnt lgkmcnt(3)
	v_mfma_f32_32x32x16_bf16 v[2:17], v[198:201], v[210:213], v[2:17]
	ds_read_b128 v[194:197], v181 offset:13408
	v_max3_f32 v224, v82, v83, v84
	v_max3_f32 v225, v98, v99, v100
	v_max3_f32 v224, v224, v85, v86
	v_max3_f32 v225, v225, v101, v102
	s_waitcnt vmcnt(2)
	ds_write_b128 v172, v[146:149] offset:22528
	v_lshl_add_u32 v222, s19, 17, v178
	global_load_dwordx4 v[146:149], v222, s[52:53]
	s_waitcnt lgkmcnt(4)
	v_mfma_f32_32x32x16_bf16 v[18:33], v[182:185], v[210:213], v[18:33]
	ds_read_b128 v[198:201], v181 offset:18016
	v_max3_f32 v224, v224, v87, v88
	v_max3_f32 v225, v225, v103, v104
	v_max3_f32 v224, v224, v89, v90
	v_max3_f32 v225, v225, v105, v106
	s_and_b64 vcc, exec, s[2:3]
	s_cbranch_vccz .Lmla_p2_nope
	ds_write_b128 v176, v[138:141] offset:22656
	v_lshl_add_u32 v222, s19, 12, v179
	global_load_dwordx4 v[138:141], v222, s[62:63]
.Lmla_p2_nope:
	s_waitcnt lgkmcnt(4)
	v_mfma_f32_32x32x16_bf16 v[2:17], v[186:189], v[214:217], v[2:17]
	ds_read_b128 v[182:185], v174
	v_max3_f32 v224, v224, v91, v92
	v_max3_f32 v225, v225, v107, v108
	v_max3_f32 v224, v224, v93, v94
	v_max3_f32 v225, v225, v109, v110
	ds_write_b128 v173, v[142:145] offset:13312
	v_lshl_add_u32 v222, s13, 7, v168
	global_load_dwordx4 v[142:145], v222, s[56:57]
	s_waitcnt lgkmcnt(5)
	v_mfma_f32_32x32x16_bf16 v[18:33], v[190:193], v[214:217], v[18:33]
	ds_read_b128 v[186:189], v174 offset:6656
	v_max3_f32 v224, v224, v95, v96
	v_max3_f32 v225, v225, v111, v112
	v_max3_f32 v224, v224, v97, v113
	v_max_f32_e32 v224, v224, v225
	s_waitcnt lgkmcnt(5)
	v_mfma_f32_32x32x16_bf16 v[2:17], v[194:197], v[218:221], v[2:17]
	ds_read_b128 v[190:193], v174 offset:32
	v_mov_b32_e32 v225, v224
	v_add_f32_e32 v1, v1, v164
	s_add_i32 s11, s11, 1
	v_permlane32_swap_b32_e32 v224, v225
	s_cmp_eq_u32 s9, s11
	v_max_f32_e32 v167, v224, v225
	s_waitcnt lgkmcnt(4)
	v_mfma_f32_32x32x16_bf16 v[18:33], v[198:201], v[218:221], v[18:33]
	ds_read_b128 v[194:197], v174 offset:6688
	v_cmp_lt_f32_e32 vcc, s66, v167
	s_waitcnt lgkmcnt(3)
	s_barrier
	s_cbranch_scc1 .Lmla_exit_p2

; template <int VAR>
; __device__ __forceinline__ void attn_phase(LAS unsigned char* lds, const AttnP P, int vcu, int G, int wave_s) {
;     ...
;                 if (ND0 == 6) {
;                     KR1(0); KR1(1); KR1(2); KR1(3); SB();
;                     QK1(0, negm); EX2(pc0, 0, w0.x); KR1(4); SB();
;                     QK1(1, negm); EX2(pc0, 2, w0.y); KR1(5); SB();
;                     QK1(2, pn0); EX2(pc0, 4, w0.z); KR1(6); SB();
;                     QK1(3, pn1); EX2(pc0, 6, w0.w); KR1(7); SB();
;                     QK1(4, pn0); EX2(pc0, 8, w1.x); KR1(8); SB();
;                     QK1(5, pn1); EX2(pc0, 10, w1.y); KR1(9); SB();
;                     QK1(6, pn0); EX2(pc0, 12, w1.z); KR1(10); SB();
;                     QK1(7, pn1); EX2(pc0, 14, w1.w); KR1(11); SB();
;                     QK1(8, pn0); EX2(pc1, 0, w2.x); VR1(0); SB();
;                     QK1(9, pn1); EX2(pc1, 2, w2.y); VR1(1); SB();
;                     QK1(10, pn0); EX2(pc1, 4, w2.z); VR1(2); SB();
;                     QK1(11, pn1); EX2(pc1, 6, w2.w); VR1(3); SB();
;                 } else {
;                     KR1(0); KR1(1); KR1(2); KR1(3); SB();
;                     QK1(0, negm); EX2(pc0, 0, w0.x); EX2(pc0, 2, w0.y); KR1(4); SB();
;                     QK1(1, negm); EX2(pc0, 4, w0.z); EX2(pc0, 6, w0.w); KR1(5); SB();
;                     QK1(2, pn0); EX2(pc0, 8, w1.x); EX2(pc0, 10, w1.y); KR1(6); SB();
;                     QK1(3, pn1); EX2(pc0, 12, w1.z); EX2(pc0, 14, w1.w); KR1(7); SB();
;                     QK1(4, pn0); EX2(pc1, 0, w2.x); VR1(0); SB();
;                     QK1(5, pn1); EX2(pc1, 2, w2.y); VR1(1); SB();
;                     QK1(6, pn0); EX2(pc1, 4, w2.z); VR1(2); SB();
;                     QK1(7, pn1); EX2(pc1, 6, w2.w); VR1(3); SB();
;                 }
;                 PV1(0, w0); EX2(pc1, 8, w3.x); VR1(4); SB();
;                 PV1(1, w0); EX2(pc1, 10, w3.y); VR1(5); SB();
;                 PV1(2, w1); EX2(pc1, 12, w3.z); VR1(6); SB();
;                 PV1(3, w1); EX2(pc1, 14, w3.w); VR1(7); SB();
;                 lrun += sacc;
;                 PV1(4, w2); MASK_TILE(pn0, pn1, t + 1); SB();
;                 PV1(5, w2); SB();
;                 PV1(6, w3); SB();
;                 PV1(7, w3); rmn = rowmax32(pn0, pn1); if (!USE_NEGM) rmn -= mref; SB();
;     ...
;             if (hn) { STOREK(t & 1); STOREV((t + 1) & 1); }
;             __syncthreads();
.Lmla_p3_go:
	v_exp_f32_e32 v222, v82
	v_exp_f32_e32 v223, v83
	v_add_f32_e32 v164, 0, v222
	v_cvt_pk_bf16_f32 v206, v222, v223
	v_add_f32_e32 v164, v223, v164
	v_exp_f32_e32 v224, v84
	v_exp_f32_e32 v225, v85
	v_add_f32_e32 v164, v224, v164
	v_cvt_pk_bf16_f32 v207, v224, v225
	v_add_f32_e32 v164, v225, v164
	s_waitcnt lgkmcnt(3)
	v_mfma_f32_32x32x16_bf16 v[34:49], v[182:185], v[114:117], v[66:81]
	ds_read_b128 v[198:201], v174 offset:64
	v_exp_f32_e32 v222, v86
	v_exp_f32_e32 v223, v87
	v_add_f32_e32 v164, v222, v164
	v_cvt_pk_bf16_f32 v208, v222, v223
	v_add_f32_e32 v164, v223, v164
	s_waitcnt lgkmcnt(3)
	v_mfma_f32_32x32x16_bf16 v[50:65], v[186:189], v[114:117], v[66:81]
	ds_read_b128 v[182:185], v174 offset:6720
	v_exp_f32_e32 v224, v88
	v_exp_f32_e32 v225, v89
	v_add_f32_e32 v164, v224, v164
	v_cvt_pk_bf16_f32 v209, v224, v225
	v_add_f32_e32 v164, v225, v164
	s_waitcnt lgkmcnt(3)
	v_mfma_f32_32x32x16_bf16 v[34:49], v[190:193], v[118:121], v[34:49]
	ds_read_b128 v[186:189], v174 offset:96
	v_exp_f32_e32 v222, v90
	v_exp_f32_e32 v223, v91
	v_add_f32_e32 v164, v222, v164
	v_cvt_pk_bf16_f32 v210, v222, v223
	v_add_f32_e32 v164, v223, v164
	s_waitcnt lgkmcnt(3)
	v_mfma_f32_32x32x16_bf16 v[50:65], v[194:197], v[118:121], v[50:65]
	ds_read_b128 v[190:193], v174 offset:6752
	v_exp_f32_e32 v224, v92
	v_exp_f32_e32 v225, v93
	v_add_f32_e32 v164, v224, v164
	v_cvt_pk_bf16_f32 v211, v224, v225
	v_add_f32_e32 v164, v225, v164
	s_waitcnt lgkmcnt(3)
	v_mfma_f32_32x32x16_bf16 v[34:49], v[198:201], v[122:125], v[34:49]
	ds_read_b128 v[194:197], v174 offset:128
	v_exp_f32_e32 v222, v94
	v_exp_f32_e32 v223, v95
	v_add_f32_e32 v164, v222, v164
	v_cvt_pk_bf16_f32 v212, v222, v223
	v_add_f32_e32 v164, v223, v164
	s_waitcnt lgkmcnt(3)
	v_mfma_f32_32x32x16_bf16 v[50:65], v[182:185], v[122:125], v[50:65]
	ds_read_b128 v[198:201], v174 offset:6784
	v_exp_f32_e32 v224, v96
	v_exp_f32_e32 v225, v97
	v_add_f32_e32 v164, v224, v164
	v_cvt_pk_bf16_f32 v213, v224, v225
	v_add_f32_e32 v164, v225, v164
	s_waitcnt lgkmcnt(3)
	v_mfma_f32_32x32x16_bf16 v[34:49], v[186:189], v[126:129], v[34:49]
	ds_read_b128 v[182:185], v174 offset:160
	v_exp_f32_e32 v222, v98
	v_exp_f32_e32 v223, v99
	v_add_f32_e32 v164, v222, v164
	v_cvt_pk_bf16_f32 v214, v222, v223
	v_add_f32_e32 v164, v223, v164
	s_waitcnt lgkmcnt(3)
	v_mfma_f32_32x32x16_bf16 v[50:65], v[190:193], v[126:129], v[50:65]
	ds_read_b128 v[186:189], v174 offset:6816
	v_exp_f32_e32 v224, v100
	v_exp_f32_e32 v225, v101
	v_add_f32_e32 v164, v224, v164
	v_cvt_pk_bf16_f32 v215, v224, v225
	v_add_f32_e32 v164, v225, v164
	s_waitcnt lgkmcnt(3)
	v_mfma_f32_32x32x16_bf16 v[34:49], v[194:197], v[130:133], v[34:49]
	ds_read_b128 v[190:193], v181 offset:35840
	v_exp_f32_e32 v222, v102
	v_exp_f32_e32 v223, v103
	v_add_f32_e32 v164, v222, v164
	v_cvt_pk_bf16_f32 v216, v222, v223
	v_add_f32_e32 v164, v223, v164
	s_waitcnt lgkmcnt(3)
	v_mfma_f32_32x32x16_bf16 v[50:65], v[198:201], v[130:133], v[50:65]
	ds_read_b128 v[194:197], v181 offset:40448
	v_exp_f32_e32 v224, v104
	v_exp_f32_e32 v225, v105
	v_add_f32_e32 v164, v224, v164
	v_cvt_pk_bf16_f32 v217, v224, v225
	v_add_f32_e32 v164, v225, v164
	s_waitcnt lgkmcnt(3)
	v_mfma_f32_32x32x16_bf16 v[34:49], v[182:185], v[134:137], v[34:49]
	ds_read_b128 v[198:201], v181 offset:35872
	v_exp_f32_e32 v222, v106
	v_exp_f32_e32 v223, v107
	v_add_f32_e32 v164, v222, v164
	v_cvt_pk_bf16_f32 v218, v222, v223
	v_add_f32_e32 v164, v223, v164
	s_waitcnt lgkmcnt(3)
	v_mfma_f32_32x32x16_bf16 v[50:65], v[186:189], v[134:137], v[50:65]
	ds_read_b128 v[182:185], v181 offset:40480
	v_exp_f32_e32 v224, v108
	v_exp_f32_e32 v225, v109
	v_add_f32_e32 v164, v224, v164
	v_cvt_pk_bf16_f32 v219, v224, v225
	v_add_f32_e32 v164, v225, v164
	s_waitcnt lgkmcnt(3)
	v_mfma_f32_32x32x16_bf16 v[2:17], v[190:193], v[206:209], v[2:17]
	ds_read_b128 v[186:189], v181 offset:35904
	v_exp_f32_e32 v222, v110
	v_exp_f32_e32 v223, v111
	v_add_f32_e32 v164, v222, v164
	v_cvt_pk_bf16_f32 v220, v222, v223
	v_add_f32_e32 v164, v223, v164
	s_waitcnt lgkmcnt(3)
	v_mfma_f32_32x32x16_bf16 v[18:33], v[194:197], v[206:209], v[18:33]
	ds_read_b128 v[190:193], v181 offset:40512
	v_exp_f32_e32 v224, v112
	v_exp_f32_e32 v225, v113
	v_add_f32_e32 v164, v224, v164
	v_cvt_pk_bf16_f32 v221, v224, v225
	v_add_f32_e32 v164, v225, v164
	s_mov_b32 s13, s19
	s_add_i32 s19, s19, 1
	s_cmp_eq_u32 s19, s9
	s_cselect_b32 s19, 0, s19
	s_waitcnt lgkmcnt(3)
	v_mfma_f32_32x32x16_bf16 v[2:17], v[198:201], v[210:213], v[2:17]
	ds_read_b128 v[194:197], v181 offset:35936
	v_max3_f32 v224, v34, v35, v36
	v_max3_f32 v225, v50, v51, v52
	v_max3_f32 v224, v224, v37, v38
	v_max3_f32 v225, v225, v53, v54
	s_waitcnt vmcnt(2)
	ds_write_b128 v172, v[150:153] offset:45056
	v_lshl_add_u32 v222, s19, 17, v178
	global_load_dwordx4 v[150:153], v222, s[52:53]
	s_waitcnt lgkmcnt(4)
	v_mfma_f32_32x32x16_bf16 v[18:33], v[182:185], v[210:213], v[18:33]
	ds_read_b128 v[198:201], v181 offset:40544
	v_max3_f32 v224, v224, v39, v40
	v_max3_f32 v225, v225, v55, v56
	v_max3_f32 v224, v224, v41, v42
	v_max3_f32 v225, v225, v57, v58
	s_and_b64 vcc, exec, s[2:3]
	s_cbranch_vccz .Lmla_p3_nope
	ds_write_b128 v176, v[160:163] offset:45184
	v_lshl_add_u32 v222, s19, 12, v179
	global_load_dwordx4 v[160:163], v222, s[62:63]
.Lmla_p3_nope:
	s_waitcnt lgkmcnt(4)
	v_mfma_f32_32x32x16_bf16 v[2:17], v[186:189], v[214:217], v[2:17]
	ds_read_b128 v[182:185], v174 offset:22528
	v_max3_f32 v224, v224, v43, v44
	v_max3_f32 v225, v225, v59, v60
	v_max3_f32 v224, v224, v45, v46
	v_max3_f32 v225, v225, v61, v62
	ds_write_b128 v173, v[202:205] offset:35840
	v_lshl_add_u32 v222, s13, 7, v168
	global_load_dwordx4 v[202:205], v222, s[56:57]
	s_waitcnt lgkmcnt(5)
	v_mfma_f32_32x32x16_bf16 v[18:33], v[190:193], v[214:217], v[18:33]
	ds_read_b128 v[186:189], v174 offset:29184
	v_max3_f32 v224, v224, v47, v48
	v_max3_f32 v225, v225, v63, v64
	v_max3_f32 v224, v224, v49, v65
	v_max_f32_e32 v224, v224, v225
	s_waitcnt lgkmcnt(5)
	v_mfma_f32_32x32x16_bf16 v[2:17], v[194:197], v[218:221], v[2:17]
	ds_read_b128 v[190:193], v174 offset:22560
	v_mov_b32_e32 v225, v224
	v_add_f32_e32 v1, v1, v164
	s_add_i32 s11, s11, 1
	v_permlane32_swap_b32_e32 v224, v225
	s_cmp_eq_u32 s9, s11
	v_max_f32_e32 v167, v224, v225
	s_waitcnt lgkmcnt(4)
	v_mfma_f32_32x32x16_bf16 v[18:33], v[198:201], v[218:221], v[18:33]
	ds_read_b128 v[194:197], v174 offset:29216
	v_cmp_lt_f32_e32 vcc, s66, v167
	s_waitcnt lgkmcnt(3)
	s_barrier
	s_cbranch_scc1 .Lmla_exit_p3
	s_branch .Lmla_p0
